# first P.V block's 8 V transpose LDS reads hoisted into the tail gaps of the QK^T section (no exposed LDS latency before the first P.V MFMA)
# baseline (speedup 1.0000x reference)
; #define MFMA32(a, b, c) __builtin_amdgcn_mfma_f32_32x32x16_bf16((a), (b), (c), 0, 0, 0)
; DI void a_finishSM(f32x16& p0, f32x16& p1, float alpha, float& l_reg, bf16x8& pa0, bf16x8& pa1, bf16x8& pa2, bf16x8& pa3) {
; #pragma unroll
;   for (int r = 0; r < 16; ++r) p1[r] = __builtin_amdgcn_exp2f(p1[r]);
;   float ps = 0;
; #pragma unroll
;   for (int r = 0; r < 16; ++r) ps += p0[r];
; #pragma unroll
;   for (int r = 0; r < 16; ++r) ps += p1[r];
;   { auto rr = __builtin_amdgcn_permlane32_swap(__float_as_uint(ps), __float_as_uint(ps), false, false);
;     ps = __uint_as_float(rr[0]) + __uint_as_float(rr[1]); }
;   l_reg = l_reg * alpha + ps;
;     ...
;   PK4(p0, 0, pa0); PK4(p0, 8, pa1); PK4(p1, 0, pa2); PK4(p1, 8, pa3);
;     ...
; }
; DI void a_qkt(f32x16& p0, f32x16& p1, const char* Ks, const char* Ps, const bf16x8* qr, const char* QP, int r32, int hi) {
;   p0 = f32x16{}; p1 = f32x16{};
; #pragma unroll
;   for (int d0 = 0; d0 < 8; ++d0) { const int cb = (d0 * 16 + hi * 8) * 2;
;     bf16x8 b0 = *reinterpret_cast<const bf16x8*>(Ks + KSWZ(r32, cb));
;     bf16x8 b1 = *reinterpret_cast<const bf16x8*>(Ks + KSWZ(32 + r32, cb));
;     p0 = MFMA32(b0, qr[d0], p0);
;     p1 = MFMA32(b1, qr[d0], p1); }
; #pragma unroll
;   for (int d0 = 0; d0 < 4; ++d0) { const int cb = (d0 * 16 + hi * 8) * 2;
;     bf16x8 b0 = *reinterpret_cast<const bf16x8*>(Ps + PSWZ(r32, cb));
;     bf16x8 b1 = *reinterpret_cast<const bf16x8*>(Ps + PSWZ(32 + r32, cb));
;     const bf16x8 qp = *reinterpret_cast<const bf16x8*>(QP + d0 * 1024);
;     p0 = MFMA32(b0, qp, p0);
;     p1 = MFMA32(b1, qp, p1); }
; }
; template <int D0> DI void pv_one(f32x16& od, int vb, bf16x8 pa0, bf16x8 pa1, bf16x8 pa2, bf16x8 pa3) {
;   const s16x4 l0 = tr_read<v_rd_off(D0, 0, 0)>(vb), h0 = tr_read<v_rd_off(D0, 0, 1)>(vb), l1 = tr_read<v_rd_off(D0, 1, 0)>(vb), h1 = tr_read<v_rd_off(D0, 1, 1)>(vb);
;   const s16x4 l2 = tr_read<v_rd_off(D0, 2, 0)>(vb), h2 = tr_read<v_rd_off(D0, 2, 1)>(vb), l3 = tr_read<v_rd_off(D0, 3, 0)>(vb), h3 = tr_read<v_rd_off(D0, 3, 1)>(vb);
.LBB0_665:
	s_mov_b32 s8, s4
	s_add_i32 s4, s7, 0
	v_add_u32_e32 v70, s4, v170
	ds_read_b128 v[66:69], v70 offset:16384
	ds_read_b128 v[82:85], v70 offset:24576
	v_add_u32_e32 v166, s4, v172
	ds_read_b128 v[202:205], v166 offset:16384
	ds_read_b128 v[206:209], v166 offset:24576
	s_waitcnt lgkmcnt(3)
	v_mfma_f32_32x32x16_bf16 v[66:81], v[66:69], v[114:117], 0
	v_exp_f32_e32 v185, v130
	v_exp_f32_e32 v186, v131
	s_waitcnt lgkmcnt(2)
	v_mfma_f32_32x32x16_bf16 v[82:97], v[82:85], v[114:117], 0
	v_add_u32_e32 v166, s4, v173
	ds_read_b128 v[214:217], v166 offset:16384
	ds_read_b128 v[218:221], v166 offset:24576
	v_exp_f32_e32 v187, v146
	v_exp_f32_e32 v188, v147
	s_waitcnt lgkmcnt(3)
	v_mfma_f32_32x32x16_bf16 v[66:81], v[202:205], v[118:121], v[66:81]
	v_exp_f32_e32 v189, v132
	v_exp_f32_e32 v190, v133
	s_waitcnt lgkmcnt(2)
	v_mfma_f32_32x32x16_bf16 v[82:97], v[206:209], v[118:121], v[82:97]
	v_add_u32_e32 v166, s4, v174
	ds_read_b128 v[202:205], v166 offset:16384
	ds_read_b128 v[206:209], v166 offset:24576
	v_exp_f32_e32 v191, v148
	v_exp_f32_e32 v192, v149
	s_waitcnt lgkmcnt(3)
	v_mfma_f32_32x32x16_bf16 v[66:81], v[214:217], v[126:129], v[66:81]
	v_exp_f32_e32 v193, v150
	v_add_f32_e32 v201, 0, v240
	v_add_f32_e32 v201, v241, v201
	s_waitcnt lgkmcnt(2)
	v_mfma_f32_32x32x16_bf16 v[82:97], v[218:221], v[126:129], v[82:97]
	v_add_u32_e32 v166, s4, v175
	ds_read_b128 v[214:217], v166 offset:16384
	ds_read_b128 v[218:221], v166 offset:24576
	v_exp_f32_e32 v194, v151
	v_add_f32_e32 v201, v242, v201
	v_add_f32_e32 v201, v243, v201
	s_waitcnt lgkmcnt(3)
	v_mfma_f32_32x32x16_bf16 v[66:81], v[202:205], v[122:125], v[66:81]
	v_exp_f32_e32 v195, v154
	v_add_f32_e32 v201, v244, v201
	v_add_f32_e32 v201, v245, v201
	s_waitcnt lgkmcnt(2)
	v_mfma_f32_32x32x16_bf16 v[82:97], v[206:209], v[122:125], v[82:97]
	v_add_u32_e32 v166, s4, v176
	ds_read_b128 v[202:205], v166 offset:16384
	ds_read_b128 v[206:209], v166 offset:24576
	v_exp_f32_e32 v196, v155
	v_add_f32_e32 v201, v246, v201
	v_add_f32_e32 v201, v247, v201
	s_waitcnt lgkmcnt(3)
	v_mfma_f32_32x32x16_bf16 v[66:81], v[214:217], v[110:113], v[66:81]
	v_exp_f32_e32 v197, v152
	v_add_f32_e32 v201, v248, v201
	v_add_f32_e32 v201, v249, v201
	s_waitcnt lgkmcnt(2)
	v_mfma_f32_32x32x16_bf16 v[82:97], v[218:221], v[110:113], v[82:97]
	v_add_u32_e32 v166, s4, v177
	ds_read_b128 v[214:217], v166 offset:16384
	ds_read_b128 v[218:221], v166 offset:24576
	v_exp_f32_e32 v198, v153
	v_add_f32_e32 v201, v250, v201
	v_add_f32_e32 v201, v251, v201
	s_waitcnt lgkmcnt(3)
	v_mfma_f32_32x32x16_bf16 v[66:81], v[202:205], v[106:109], v[66:81]
	v_exp_f32_e32 v199, v156
	v_add_f32_e32 v201, v252, v201
	v_add_f32_e32 v201, v253, v201
	s_waitcnt lgkmcnt(2)
	v_mfma_f32_32x32x16_bf16 v[82:97], v[206:209], v[106:109], v[82:97]
	v_add_u32_e32 v166, s4, v178
	ds_read_b128 v[202:205], v166 offset:16384
	ds_read_b128 v[206:209], v166 offset:24576
	v_exp_f32_e32 v200, v157
	v_add_f32_e32 v201, v254, v201
	v_add_f32_e32 v201, v255, v201
	s_waitcnt lgkmcnt(3)
	v_mfma_f32_32x32x16_bf16 v[66:81], v[214:217], v[102:105], v[66:81]
	v_add_f32_e32 v201, v185, v201
	v_add_f32_e32 v201, v186, v201
	v_cvt_pk_bf16_f32 v130, v240, v241
	s_waitcnt lgkmcnt(2)
	v_mfma_f32_32x32x16_bf16 v[82:97], v[218:221], v[102:105], v[82:97]
	v_add_u32_e32 v166, s4, v179
	ds_read_b128 v[214:217], v166 offset:32768
	ds_read_b128 v[218:221], v166 offset:36864
	ds_read_b128 v[222:225], v163
	v_add_f32_e32 v201, v187, v201
	v_add_f32_e32 v201, v188, v201
	v_cvt_pk_bf16_f32 v131, v242, v243
	s_waitcnt lgkmcnt(4)
	v_mfma_f32_32x32x16_bf16 v[66:81], v[202:205], v[98:101], v[66:81]
	v_add_f32_e32 v201, v189, v201
	v_add_f32_e32 v201, v190, v201
	v_cvt_pk_bf16_f32 v132, v244, v245
	s_waitcnt lgkmcnt(3)
	v_mfma_f32_32x32x16_bf16 v[82:97], v[206:209], v[98:101], v[82:97]
	v_add_u32_e32 v166, s4, v180
	ds_read_b128 v[202:205], v166 offset:32768
	ds_read_b128 v[206:209], v166 offset:36864
	ds_read_b128 v[210:213], v163 offset:1024
	v_add_f32_e32 v201, v191, v201
	v_add_f32_e32 v201, v192, v201
	v_cvt_pk_bf16_f32 v133, v246, v247
	s_waitcnt lgkmcnt(3)
	v_mfma_f32_32x32x16_bf16 v[66:81], v[214:217], v[222:225], v[66:81]
	v_add_f32_e32 v201, v193, v201
	v_add_f32_e32 v201, v194, v201
	v_cvt_pk_bf16_f32 v154, v248, v249
	v_mfma_f32_32x32x16_bf16 v[82:97], v[218:221], v[222:225], v[82:97]
	v_add_u32_e32 v166, s4, v181
	ds_read_b128 v[214:217], v166 offset:32768
	ds_read_b128 v[218:221], v166 offset:36864
	ds_read_b128 v[222:225], v163 offset:2048
	v_add_f32_e32 v201, v195, v201
	v_add_f32_e32 v201, v196, v201
	v_cvt_pk_bf16_f32 v155, v250, v251
	s_waitcnt lgkmcnt(3)
	v_mfma_f32_32x32x16_bf16 v[66:81], v[202:205], v[210:213], v[66:81]
	v_add_f32_e32 v201, v197, v201
	v_add_f32_e32 v201, v198, v201
	v_cvt_pk_bf16_f32 v156, v252, v253
	v_mfma_f32_32x32x16_bf16 v[82:97], v[206:209], v[210:213], v[82:97]
	v_add_u32_e32 v166, s4, v182
	ds_read_b128 v[202:205], v166 offset:32768
	ds_read_b128 v[206:209], v166 offset:36864
	ds_read_b128 v[210:213], v163 offset:3072
	v_add_f32_e32 v201, v199, v201
	v_add_f32_e32 v150, v200, v201
	v_cvt_pk_bf16_f32 v157, v254, v255
	s_waitcnt lgkmcnt(3)
	v_mfma_f32_32x32x16_bf16 v[66:81], v[214:217], v[222:225], v[66:81]
	v_mov_b32_e32 v151, v150
	v_cvt_pk_bf16_f32 v184, v185, v186
	v_cvt_pk_bf16_f32 v185, v187, v188
	v_permlane32_swap_b32_e32 v130, v132
	v_mfma_f32_32x32x16_bf16 v[82:97], v[218:221], v[222:225], v[82:97]
	v_add_u32_e32 v166, s8, v171
	ds_read_b64_tr_b16 v[214:215], v166 offset:2048
	ds_read_b64_tr_b16 v[216:217], v166 offset:4096
	ds_read_b64_tr_b16 v[218:219], v166 offset:6144
	ds_read_b64_tr_b16 v[220:221], v166 offset:8192
	ds_read_b64_tr_b16 v[222:223], v166 offset:10240
	ds_read_b64_tr_b16 v[224:225], v166 offset:12288
	ds_read_b64_tr_b16 v[226:227], v166 offset:14336
	v_cvt_pk_bf16_f32 v186, v189, v190
	v_cvt_pk_bf16_f32 v187, v191, v192
	v_permlane32_swap_b32_e32 v150, v151
	v_permlane32_swap_b32_e32 v131, v133
	s_waitcnt lgkmcnt(7)
; DI void pv_sm(f32x16* o, int vb, bf16x8 pa0, bf16x8 pa1, bf16x8 pa2, bf16x8 pa3, f32x16& p0, f32x16& p1, float& m_reg, float& mn, float& alpha) {
;   PV_BLOCK(0)
;   float pm0 = p0[0];
; #pragma unroll
;   for (int r = 1; r < 16; ++r) pm0 = fmaxf(pm0, p0[r]);
;   PV_BLOCK(1)
;   float pmax = pm0;
; #pragma unroll
;   for (int r = 0; r < 16; ++r) pmax = fmaxf(pmax, p1[r]);
;   { auto rr = __builtin_amdgcn_permlane32_swap(__float_as_uint(pmax), __float_as_uint(pmax), false, false);
;     pmax = fmaxf(__uint_as_float(rr[0]), __uint_as_float(rr[1])); }
;   const bool keep = __all(pmax - m_reg <= ATH);
;   mn = keep ? m_reg : fmaxf(m_reg, pmax);
;   alpha = __builtin_amdgcn_exp2f(m_reg - mn);
;   m_reg = mn;
;   PV_BLOCK(2)
; #pragma unroll
;   for (int r = 0; r < 16; ++r) { p0[r] = p0[r] - mn; p1[r] = p1[r] - mn; }
;   PV_BLOCK(3)
; #pragma unroll
;   for (int r = 0; r < 16; ++r) p0[r] = __builtin_amdgcn_exp2f(p0[r]);
; }
	v_mfma_f32_32x32x16_bf16 v[66:81], v[202:205], v[210:213], v[66:81]
	v_cvt_pk_bf16_f32 v188, v193, v194
	v_cvt_pk_bf16_f32 v189, v195, v196
	v_permlane32_swap_b32_e32 v154, v156
	v_mfma_f32_32x32x16_bf16 v[82:97], v[206:209], v[210:213], v[82:97]
	ds_read_b64_tr_b16 v[212:213], v166 offset:0
	v_cvt_pk_bf16_f32 v190, v197, v198
	v_cvt_pk_bf16_f32 v191, v199, v200
	v_permlane32_swap_b32_e32 v155, v157
	s_nop 0
	v_permlane32_swap_b32_e32 v184, v186
	v_permlane32_swap_b32_e32 v185, v187
	v_permlane32_swap_b32_e32 v188, v190
	v_permlane32_swap_b32_e32 v189, v191
	v_lshl_add_u64 v[146:147], s[84:85], 0, v[142:143]
	v_add_co_u32_e32 v148, vcc, s56, v146
	s_nop 1
	v_addc_co_u32_e32 v149, vcc, 0, v147, vcc
	v_add_co_u32_e32 v152, vcc, s57, v146
	s_nop 1
	v_addc_co_u32_e32 v153, vcc, 0, v147, vcc
	global_load_dwordx4 v[192:195], v[148:149], off offset:256
	global_load_dwordx4 v[196:199], v[148:149], off
	global_load_dwordx4 v[200:203], v[152:153], off offset:256
	global_load_dwordx4 v[204:207], v[152:153], off
	v_lshl_add_u64 v[148:149], s[84:85], 0, v[140:141]
	v_add_co_u32_e32 v152, vcc, s58, v148
	s_nop 1
	v_addc_co_u32_e32 v153, vcc, 0, v149, vcc
	global_load_dwordx4 v[208:211], v[152:153], off
	v_add_u32_e32 v166, s8, v171
	s_waitcnt lgkmcnt(0)
	s_nop 0
	v_mfma_f32_32x32x16_bf16 v[2:17], v[130:133], v[212:215], v[2:17]
	ds_read_b64_tr_b16 v[212:213], v166 offset:0x200
	ds_read_b64_tr_b16 v[214:215], v166 offset:0xa00
	v_max_f32_e32 v152, v67, v67
	v_max_f32_e32 v153, v66, v66
	v_max_f32_e32 v152, v153, v152
	v_max3_f32 v152, v152, v68, v69
	v_max3_f32 v152, v152, v70, v71
	v_mfma_f32_32x32x16_bf16 v[2:17], v[154:157], v[216:219], v[2:17]
	ds_read_b64_tr_b16 v[216:217], v166 offset:0x1200
	ds_read_b64_tr_b16 v[218:219], v166 offset:0x1a00
	v_max3_f32 v152, v152, v72, v73
	v_max3_f32 v152, v152, v74, v75
	v_max3_f32 v152, v152, v76, v77
	v_max3_f32 v152, v152, v78, v79
	v_max3_f32 v152, v152, v80, v81
	v_mfma_f32_32x32x16_bf16 v[2:17], v[184:187], v[220:223], v[2:17]
	ds_read_b64_tr_b16 v[220:221], v166 offset:0x2200
	ds_read_b64_tr_b16 v[222:223], v166 offset:0x2a00
	ds_read_b64_tr_b16 v[228:229], v166 offset:0x3200
	ds_read_b64_tr_b16 v[230:231], v166 offset:0x3a00
	s_waitcnt lgkmcnt(0)
	v_mfma_f32_32x32x16_bf16 v[2:17], v[188:191], v[224:227], v[2:17]
	v_mfma_f32_32x32x16_bf16 v[50:65], v[130:133], v[212:215], v[50:65]
	v_max3_f32 v152, v152, v82, v83
	v_max3_f32 v152, v152, v84, v85
	v_max3_f32 v152, v152, v86, v87
	v_max3_f32 v152, v152, v88, v89
	v_max3_f32 v152, v152, v90, v91
	v_max3_f32 v152, v152, v92, v93
	v_max3_f32 v152, v152, v94, v95
	v_mfma_f32_32x32x16_bf16 v[50:65], v[154:157], v[216:219], v[50:65]
	v_max3_f32 v152, v152, v96, v97
	v_mov_b32_e32 v153, v152
	s_nop 1
	v_permlane32_swap_b32_e32 v152, v153
	v_max_f32_e32 v153, v153, v153
	v_max_f32_e32 v152, v152, v152
	v_max_f32_e32 v152, v152, v153
	v_mfma_f32_32x32x16_bf16 v[50:65], v[184:187], v[220:223], v[50:65]
	ds_read_b64_tr_b16 v[212:213], v166 offset:0x400
	v_sub_f32_e32 v153, v152, v144
	ds_read_b64_tr_b16 v[214:215], v166 offset:0xc00
	v_cmp_ge_f32_e32 vcc, s54, v153
	ds_read_b64_tr_b16 v[216:217], v166 offset:0x1400
	s_cmp_eq_u64 vcc, exec
	v_max_f32_e32 v153, v144, v144
	ds_read_b64_tr_b16 v[218:219], v166 offset:0x1c00
	v_mfma_f32_32x32x16_bf16 v[50:65], v[188:191], v[228:231], v[50:65]
	v_max_f32_e32 v152, v153, v152
	s_cselect_b64 vcc, -1, 0
	ds_read_b64_tr_b16 v[220:221], v166 offset:0x2400
	v_cndmask_b32_e32 v153, v152, v144, vcc
	ds_read_b64_tr_b16 v[222:223], v166 offset:0x2c00
	v_sub_f32_e32 v144, v144, v153
	ds_read_b64_tr_b16 v[224:225], v166 offset:0x3400
	v_exp_f32_e32 v152, v144
	ds_read_b64_tr_b16 v[226:227], v166 offset:0x3c00
	s_waitcnt lgkmcnt(0)
	v_mfma_f32_32x32x16_bf16 v[34:49], v[130:133], v[212:215], v[34:49]
	ds_read_b64_tr_b16 v[212:213], v166 offset:0x600
	ds_read_b64_tr_b16 v[214:215], v166 offset:0xe00
	v_sub_f32_e32 v66, v66, v153
	v_sub_f32_e32 v67, v67, v153
	v_sub_f32_e32 v68, v68, v153
	v_sub_f32_e32 v69, v69, v153
	v_mfma_f32_32x32x16_bf16 v[34:49], v[154:157], v[216:219], v[34:49]
	ds_read_b64_tr_b16 v[216:217], v166 offset:0x1600
	ds_read_b64_tr_b16 v[218:219], v166 offset:0x1e00
	v_sub_f32_e32 v70, v70, v153
	v_sub_f32_e32 v71, v71, v153
	v_exp_f32_e32 v240, v66
	v_exp_f32_e32 v241, v67
	v_mfma_f32_32x32x16_bf16 v[34:49], v[184:187], v[220:223], v[34:49]
	ds_read_b64_tr_b16 v[220:221], v166 offset:0x2600
	ds_read_b64_tr_b16 v[222:223], v166 offset:0x2e00
	ds_read_b64_tr_b16 v[228:229], v166 offset:0x3600
	ds_read_b64_tr_b16 v[230:231], v166 offset:0x3e00
	v_sub_f32_e32 v72, v72, v153
	v_sub_f32_e32 v73, v73, v153
	v_exp_f32_e32 v242, v68
	v_exp_f32_e32 v243, v69
	s_waitcnt lgkmcnt(0)
	v_mfma_f32_32x32x16_bf16 v[34:49], v[188:191], v[224:227], v[34:49]
	v_sub_f32_e32 v74, v74, v153
	v_sub_f32_e32 v75, v75, v153
	v_exp_f32_e32 v244, v70
	v_exp_f32_e32 v245, v71
	v_mfma_f32_32x32x16_bf16 v[18:33], v[130:133], v[212:215], v[18:33]
	v_sub_f32_e32 v76, v76, v153
	v_sub_f32_e32 v77, v77, v153
	v_exp_f32_e32 v246, v72
	v_exp_f32_e32 v247, v73
	s_add_i32 s9, s6, 0
	v_add_u32_e32 v130, s9, v164
	s_waitcnt vmcnt(0)
	s_waitcnt vmcnt(4)
	ds_write_b128 v130, v[192:195]
	v_add_u32_e32 v130, s9, v165
	s_waitcnt vmcnt(2)
	ds_write_b128 v130, v[200:203]
	v_add_u32_e32 v130, s9, v167
	v_mfma_f32_32x32x16_bf16 v[18:33], v[154:157], v[216:219], v[18:33]
	ds_write_b128 v130, v[196:199] offset:16384
	v_add_u32_e32 v130, s9, v168
	s_waitcnt vmcnt(1)
	ds_write_b128 v130, v[204:207] offset:16384
	v_add_u32_e32 v130, s9, v169
	v_cmp_gt_f32_e32 vcc, 1.0, v152
	s_waitcnt vmcnt(0)
	ds_write_b128 v130, v[208:211] offset:32768
	v_sub_f32_e32 v78, v78, v153
	v_sub_f32_e32 v79, v79, v153
	v_exp_f32_e32 v248, v74
	v_exp_f32_e32 v249, v75
	v_mfma_f32_32x32x16_bf16 v[18:33], v[184:187], v[220:223], v[18:33]
	v_sub_f32_e32 v80, v80, v153
	v_sub_f32_e32 v81, v81, v153
	v_exp_f32_e32 v250, v76
	v_exp_f32_e32 v251, v77
	v_mfma_f32_32x32x16_bf16 v[18:33], v[188:191], v[228:231], v[18:33]
	v_exp_f32_e32 v252, v78
	v_exp_f32_e32 v253, v79
	v_exp_f32_e32 v254, v80
	v_exp_f32_e32 v255, v81
	s_cbranch_vccz .LBB0_669
; #define MFMA32(a, b, c) __builtin_amdgcn_mfma_f32_32x32x16_bf16((a), (b), (c), 0, 0, 0)
; DI void a_qkt(f32x16& p0, f32x16& p1, const char* Ks, const char* Ps, const bf16x8* qr, const char* QP, int r32, int hi) {
;   p0 = f32x16{}; p1 = f32x16{};
; #pragma unroll
;   for (int d0 = 0; d0 < 8; ++d0) { const int cb = (d0 * 16 + hi * 8) * 2;
;     bf16x8 b0 = *reinterpret_cast<const bf16x8*>(Ks + KSWZ(r32, cb));
;     bf16x8 b1 = *reinterpret_cast<const bf16x8*>(Ks + KSWZ(32 + r32, cb));
;     p0 = MFMA32(b0, qr[d0], p0);
;     p1 = MFMA32(b1, qr[d0], p1); }
; #pragma unroll
;   for (int d0 = 0; d0 < 4; ++d0) { const int cb = (d0 * 16 + hi * 8) * 2;
;     bf16x8 b0 = *reinterpret_cast<const bf16x8*>(Ps + PSWZ(r32, cb));
;     bf16x8 b1 = *reinterpret_cast<const bf16x8*>(Ps + PSWZ(32 + r32, cb));
;     const bf16x8 qp = *reinterpret_cast<const bf16x8*>(QP + d0 * 1024);
;     p0 = MFMA32(b0, qp, p0);
;     p1 = MFMA32(b1, qp, p1); }
; }
	s_and_saveexec_b64 s[4:5], s[2:3]
	ds_write_b32 v161, v152 offset:128
	s_or_b64 exec, exec, s[4:5]
	s_waitcnt lgkmcnt(0)
	v_add_u32_e32 v144, v137, v134
	ds_read_b128 v[130:133], v144 offset:224
	ds_read_b128 v[154:157], v144 offset:192
	ds_read_b128 v[184:187], v144 offset:160
	ds_read_b128 v[188:191], v144 offset:128
	s_waitcnt lgkmcnt(3)
	v_pk_mul_f32 v[14:15], v[14:15], v[130:131]
	s_waitcnt lgkmcnt(2)
	v_pk_mul_f32 v[10:11], v[10:11], v[154:155]
	s_waitcnt lgkmcnt(1)
	v_pk_mul_f32 v[6:7], v[6:7], v[184:185]
	v_pk_mul_f32 v[16:17], v[16:17], v[132:133]
	v_pk_mul_f32 v[12:13], v[12:13], v[156:157]
	v_pk_mul_f32 v[8:9], v[8:9], v[186:187]
	s_waitcnt lgkmcnt(0)
	v_pk_mul_f32 v[4:5], v[4:5], v[190:191]
	v_pk_mul_f32 v[2:3], v[2:3], v[188:189]
	v_pk_mul_f32 v[62:63], v[62:63], v[130:131]
	v_pk_mul_f32 v[58:59], v[58:59], v[154:155]
	v_pk_mul_f32 v[54:55], v[54:55], v[184:185]
	v_pk_mul_f32 v[64:65], v[64:65], v[132:133]
	v_pk_mul_f32 v[60:61], v[60:61], v[156:157]
	v_pk_mul_f32 v[56:57], v[56:57], v[186:187]
	v_pk_mul_f32 v[52:53], v[52:53], v[190:191]
	v_pk_mul_f32 v[50:51], v[50:51], v[188:189]
	v_pk_mul_f32 v[46:47], v[46:47], v[130:131]
	v_pk_mul_f32 v[42:43], v[42:43], v[154:155]
	v_pk_mul_f32 v[38:39], v[38:39], v[184:185]
	v_pk_mul_f32 v[48:49], v[48:49], v[132:133]
	v_pk_mul_f32 v[44:45], v[44:45], v[156:157]
	v_pk_mul_f32 v[40:41], v[40:41], v[186:187]
	v_pk_mul_f32 v[36:37], v[36:37], v[190:191]
	v_pk_mul_f32 v[34:35], v[34:35], v[188:189]
	v_pk_mul_f32 v[30:31], v[30:31], v[130:131]
	v_pk_mul_f32 v[26:27], v[26:27], v[154:155]
	v_pk_mul_f32 v[22:23], v[22:23], v[184:185]
	v_pk_mul_f32 v[32:33], v[32:33], v[132:133]
	v_pk_mul_f32 v[28:29], v[28:29], v[156:157]
	v_pk_mul_f32 v[24:25], v[24:25], v[186:187]
	v_pk_mul_f32 v[20:21], v[20:21], v[190:191]
	v_pk_mul_f32 v[18:19], v[18:19], v[188:189]
.LBB0_669:
	s_waitcnt lgkmcnt(0)
	s_barrier
	v_add_u32_e32 v70, s9, v170
	ds_read_b128 v[66:69], v70 offset:16384
	ds_read_b128 v[70:73], v70 offset:24576
	v_add_u32_e32 v226, s9, v172
	ds_read_b128 v[204:207], v226 offset:16384
	ds_read_b128 v[208:211], v226 offset:24576
	v_sub_f32_e32 v144, v82, v153
	v_sub_f32_e32 v188, v83, v153
	v_sub_f32_e32 v189, v84, v153
	v_sub_f32_e32 v190, v85, v153
	v_sub_f32_e32 v191, v86, v153
	v_sub_f32_e32 v192, v87, v153
	v_sub_f32_e32 v193, v88, v153
	v_sub_f32_e32 v194, v89, v153
	v_sub_f32_e32 v195, v90, v153
	v_sub_f32_e32 v196, v91, v153
	v_sub_f32_e32 v197, v92, v153
	v_sub_f32_e32 v198, v93, v153
	v_sub_f32_e32 v199, v94, v153
	v_sub_f32_e32 v200, v95, v153
	v_sub_f32_e32 v201, v96, v153
	v_sub_f32_e32 v202, v97, v153
	s_waitcnt lgkmcnt(3)
	v_mfma_f32_32x32x16_bf16 v[82:97], v[66:69], v[114:117], 0
	v_exp_f32_e32 v144, v144
	v_exp_f32_e32 v156, v188
	s_waitcnt lgkmcnt(2)
	v_mfma_f32_32x32x16_bf16 v[66:81], v[70:73], v[114:117], 0
	v_add_u32_e32 v226, s9, v173
	ds_read_b128 v[216:219], v226 offset:16384
	ds_read_b128 v[220:223], v226 offset:24576
	v_exp_f32_e32 v157, v189
	v_exp_f32_e32 v184, v190
	s_waitcnt lgkmcnt(3)
	v_mfma_f32_32x32x16_bf16 v[82:97], v[204:207], v[118:121], v[82:97]
	v_exp_f32_e32 v185, v191
	v_exp_f32_e32 v192, v192
	s_waitcnt lgkmcnt(2)
	v_mfma_f32_32x32x16_bf16 v[66:81], v[208:211], v[118:121], v[66:81]
	v_add_u32_e32 v226, s9, v174
	ds_read_b128 v[204:207], v226 offset:16384
	ds_read_b128 v[208:211], v226 offset:24576
	v_exp_f32_e32 v193, v193
	v_exp_f32_e32 v194, v194
	s_waitcnt lgkmcnt(3)
	v_mfma_f32_32x32x16_bf16 v[82:97], v[216:219], v[126:129], v[82:97]
	v_exp_f32_e32 v195, v195
	v_add_f32_e32 v203, 0, v240
	v_add_f32_e32 v203, v241, v203
	s_waitcnt lgkmcnt(2)
	v_mfma_f32_32x32x16_bf16 v[66:81], v[220:223], v[126:129], v[66:81]
	v_add_u32_e32 v226, s9, v175
	ds_read_b128 v[216:219], v226 offset:16384
	ds_read_b128 v[220:223], v226 offset:24576
	v_exp_f32_e32 v196, v196
	v_add_f32_e32 v203, v242, v203
	v_add_f32_e32 v203, v243, v203
	s_waitcnt lgkmcnt(3)
	v_mfma_f32_32x32x16_bf16 v[82:97], v[204:207], v[122:125], v[82:97]
	v_exp_f32_e32 v197, v197
	v_add_f32_e32 v203, v244, v203
	v_add_f32_e32 v203, v245, v203
	s_waitcnt lgkmcnt(2)
	v_mfma_f32_32x32x16_bf16 v[66:81], v[208:211], v[122:125], v[66:81]
	v_add_u32_e32 v226, s9, v176
	ds_read_b128 v[204:207], v226 offset:16384
	ds_read_b128 v[208:211], v226 offset:24576
	v_exp_f32_e32 v198, v198
	v_add_f32_e32 v203, v246, v203
	v_add_f32_e32 v203, v247, v203
	s_waitcnt lgkmcnt(3)
	v_mfma_f32_32x32x16_bf16 v[82:97], v[216:219], v[110:113], v[82:97]
	v_exp_f32_e32 v199, v199
	v_add_f32_e32 v203, v248, v203
	v_add_f32_e32 v203, v249, v203
	s_waitcnt lgkmcnt(2)
	v_mfma_f32_32x32x16_bf16 v[66:81], v[220:223], v[110:113], v[66:81]
	v_add_u32_e32 v226, s9, v177
	ds_read_b128 v[216:219], v226 offset:16384
	ds_read_b128 v[220:223], v226 offset:24576
	v_exp_f32_e32 v200, v200
	v_add_f32_e32 v203, v250, v203
	v_add_f32_e32 v203, v251, v203
	s_waitcnt lgkmcnt(3)
	v_mfma_f32_32x32x16_bf16 v[82:97], v[204:207], v[106:109], v[82:97]
	v_exp_f32_e32 v201, v201
	v_add_f32_e32 v203, v252, v203
	v_add_f32_e32 v203, v253, v203
	s_waitcnt lgkmcnt(2)
	v_mfma_f32_32x32x16_bf16 v[66:81], v[208:211], v[106:109], v[66:81]
	v_add_u32_e32 v226, s9, v178
	ds_read_b128 v[204:207], v226 offset:16384
	ds_read_b128 v[208:211], v226 offset:24576
	v_exp_f32_e32 v202, v202
	v_add_f32_e32 v203, v254, v203
	v_add_f32_e32 v203, v255, v203
	s_waitcnt lgkmcnt(3)
	v_mfma_f32_32x32x16_bf16 v[82:97], v[216:219], v[102:105], v[82:97]
	v_add_f32_e32 v203, v144, v203
	v_add_f32_e32 v203, v156, v203
	v_cvt_pk_bf16_f32 v130, v240, v241
	s_waitcnt lgkmcnt(2)
; #define MFMA32(a, b, c) __builtin_amdgcn_mfma_f32_32x32x16_bf16((a), (b), (c), 0, 0, 0)
; DI void a_qkt(f32x16& p0, f32x16& p1, const char* Ks, const char* Ps, const bf16x8* qr, const char* QP, int r32, int hi) {
;   p0 = f32x16{}; p1 = f32x16{};
; #pragma unroll
;   for (int d0 = 0; d0 < 8; ++d0) { const int cb = (d0 * 16 + hi * 8) * 2;
;     bf16x8 b0 = *reinterpret_cast<const bf16x8*>(Ks + KSWZ(r32, cb));
;     bf16x8 b1 = *reinterpret_cast<const bf16x8*>(Ks + KSWZ(32 + r32, cb));
;     p0 = MFMA32(b0, qr[d0], p0);
;     p1 = MFMA32(b1, qr[d0], p1); }
; #pragma unroll
;   for (int d0 = 0; d0 < 4; ++d0) { const int cb = (d0 * 16 + hi * 8) * 2;
;     bf16x8 b0 = *reinterpret_cast<const bf16x8*>(Ps + PSWZ(r32, cb));
;     bf16x8 b1 = *reinterpret_cast<const bf16x8*>(Ps + PSWZ(32 + r32, cb));
;     const bf16x8 qp = *reinterpret_cast<const bf16x8*>(QP + d0 * 1024);
;     p0 = MFMA32(b0, qp, p0);
;     p1 = MFMA32(b1, qp, p1); }
; }
; DI void pv_sm(f32x16* o, int vb, bf16x8 pa0, bf16x8 pa1, bf16x8 pa2, bf16x8 pa3, f32x16& p0, f32x16& p1, float& m_reg, float& mn, float& alpha) {
;   PV_BLOCK(0)
	v_mfma_f32_32x32x16_bf16 v[66:81], v[220:223], v[102:105], v[66:81]
	v_add_u32_e32 v226, s9, v179
	ds_read_b128 v[216:219], v226 offset:32768
	ds_read_b128 v[220:223], v226 offset:36864
	ds_read_b128 v[228:231], v163
	v_add_f32_e32 v203, v157, v203
	v_add_f32_e32 v203, v184, v203
	v_cvt_pk_bf16_f32 v131, v242, v243
	s_waitcnt lgkmcnt(4)
	v_mfma_f32_32x32x16_bf16 v[82:97], v[204:207], v[98:101], v[82:97]
	v_add_f32_e32 v203, v185, v203
	v_add_f32_e32 v203, v192, v203
	v_cvt_pk_bf16_f32 v132, v244, v245
	s_waitcnt lgkmcnt(3)
	v_mfma_f32_32x32x16_bf16 v[66:81], v[208:211], v[98:101], v[66:81]
	v_add_u32_e32 v226, s9, v180
	ds_read_b128 v[204:207], v226 offset:32768
	ds_read_b128 v[208:211], v226 offset:36864
	ds_read_b128 v[212:215], v163 offset:1024
	v_add_f32_e32 v203, v193, v203
	v_add_f32_e32 v203, v194, v203
	v_cvt_pk_bf16_f32 v133, v246, v247
	s_waitcnt lgkmcnt(3)
	v_mfma_f32_32x32x16_bf16 v[82:97], v[216:219], v[228:231], v[82:97]
	v_add_f32_e32 v203, v195, v203
	v_add_f32_e32 v203, v196, v203
	v_cvt_pk_bf16_f32 v186, v248, v249
	v_mfma_f32_32x32x16_bf16 v[66:81], v[220:223], v[228:231], v[66:81]
	v_add_u32_e32 v226, s9, v181
	ds_read_b128 v[216:219], v226 offset:32768
	ds_read_b128 v[220:223], v226 offset:36864
	ds_read_b128 v[228:231], v163 offset:2048
	v_add_f32_e32 v203, v197, v203
	v_add_f32_e32 v203, v198, v203
	v_cvt_pk_bf16_f32 v187, v250, v251
	s_waitcnt lgkmcnt(3)
	v_mfma_f32_32x32x16_bf16 v[82:97], v[204:207], v[212:215], v[82:97]
	v_add_f32_e32 v203, v199, v203
	v_add_f32_e32 v203, v200, v203
	v_cvt_pk_bf16_f32 v188, v252, v253
	v_mfma_f32_32x32x16_bf16 v[66:81], v[208:211], v[212:215], v[66:81]
	v_add_u32_e32 v226, s9, v182
	ds_read_b128 v[204:207], v226 offset:32768
	ds_read_b128 v[208:211], v226 offset:36864
	ds_read_b128 v[212:215], v163 offset:3072
	v_add_f32_e32 v203, v201, v203
	v_add_f32_e32 v154, v202, v203
	v_cvt_pk_bf16_f32 v189, v254, v255
	s_waitcnt lgkmcnt(3)
	v_mfma_f32_32x32x16_bf16 v[82:97], v[216:219], v[228:231], v[82:97]
	v_mov_b32_e32 v155, v154
	v_cvt_pk_bf16_f32 v190, v144, v156
	v_cvt_pk_bf16_f32 v191, v157, v184
	v_permlane32_swap_b32_e32 v130, v132
	v_mfma_f32_32x32x16_bf16 v[66:81], v[220:223], v[228:231], v[66:81]
	v_add_u32_e32 v232, s7, v171
	ds_read_b64_tr_b16 v[216:217], v232 offset:2048
	ds_read_b64_tr_b16 v[218:219], v232 offset:4096
	ds_read_b64_tr_b16 v[220:221], v232 offset:6144
	ds_read_b64_tr_b16 v[222:223], v232 offset:8192
	ds_read_b64_tr_b16 v[224:225], v232 offset:10240
	ds_read_b64_tr_b16 v[226:227], v232 offset:12288
	ds_read_b64_tr_b16 v[228:229], v232 offset:14336
	v_cvt_pk_bf16_f32 v192, v185, v192
	v_cvt_pk_bf16_f32 v193, v193, v194
	v_permlane32_swap_b32_e32 v154, v155
	v_permlane32_swap_b32_e32 v131, v133
	s_waitcnt lgkmcnt(7)
	v_mfma_f32_32x32x16_bf16 v[82:97], v[204:207], v[212:215], v[82:97]
	v_cvt_pk_bf16_f32 v194, v195, v196
	v_cvt_pk_bf16_f32 v195, v197, v198
	v_permlane32_swap_b32_e32 v186, v188
	v_mfma_f32_32x32x16_bf16 v[66:81], v[208:211], v[212:215], v[66:81]
	ds_read_b64_tr_b16 v[214:215], v232 offset:0
	v_cvt_pk_bf16_f32 v196, v199, v200
	v_cvt_pk_bf16_f32 v197, v201, v202
	v_permlane32_swap_b32_e32 v187, v189
	s_nop 0
	v_permlane32_swap_b32_e32 v190, v192
	v_permlane32_swap_b32_e32 v191, v193
	v_permlane32_swap_b32_e32 v194, v196
	v_permlane32_swap_b32_e32 v195, v197
	v_add_co_u32_e32 v156, vcc, s59, v146
	s_nop 1
	v_addc_co_u32_e32 v157, vcc, 0, v147, vcc
	v_add_co_u32_e32 v146, vcc, s60, v146
	s_nop 1
	v_addc_co_u32_e32 v147, vcc, 0, v147, vcc
	global_load_dwordx4 v[198:201], v[156:157], off offset:256
	global_load_dwordx4 v[202:205], v[156:157], off
	global_load_dwordx4 v[206:209], v[146:147], off offset:256
	global_load_dwordx4 v[210:213], v[146:147], off
	v_add_co_u32_e32 v146, vcc, s61, v148
	s_nop 1
	v_addc_co_u32_e32 v147, vcc, 0, v149, vcc
	global_load_dwordx4 v[146:149], v[146:147], off
	v_add_u32_e32 v156, s7, v171
	s_waitcnt lgkmcnt(0)
	s_nop 0
	v_mfma_f32_32x32x16_bf16 v[2:17], v[130:133], v[214:217], v[2:17]
	ds_read_b64_tr_b16 v[214:215], v156 offset:0x200
	ds_read_b64_tr_b16 v[216:217], v156 offset:0xa00
	v_max_f32_e32 v144, v83, v83
	v_max_f32_e32 v157, v82, v82
	v_max_f32_e32 v144, v157, v144
	v_max3_f32 v144, v144, v84, v85
	v_max3_f32 v144, v144, v86, v87
	v_mfma_f32_32x32x16_bf16 v[2:17], v[186:189], v[218:221], v[2:17]
	ds_read_b64_tr_b16 v[218:219], v156 offset:0x1200
	ds_read_b64_tr_b16 v[220:221], v156 offset:0x1a00
	v_max3_f32 v144, v144, v88, v89
	v_max3_f32 v144, v144, v90, v91
	v_max3_f32 v144, v144, v92, v93
	v_max3_f32 v144, v144, v94, v95
	v_max3_f32 v144, v144, v96, v97
	v_mfma_f32_32x32x16_bf16 v[2:17], v[190:193], v[222:225], v[2:17]
	ds_read_b64_tr_b16 v[222:223], v156 offset:0x2200
	ds_read_b64_tr_b16 v[224:225], v156 offset:0x2a00
	ds_read_b64_tr_b16 v[230:231], v156 offset:0x3200
	ds_read_b64_tr_b16 v[232:233], v156 offset:0x3a00
	s_waitcnt lgkmcnt(0)
; DI void pv_sm(f32x16* o, int vb, bf16x8 pa0, bf16x8 pa1, bf16x8 pa2, bf16x8 pa3, f32x16& p0, f32x16& p1, float& m_reg, float& mn, float& alpha) {
;   PV_BLOCK(0)
;   float pm0 = p0[0];
; #pragma unroll
;   for (int r = 1; r < 16; ++r) pm0 = fmaxf(pm0, p0[r]);
;   PV_BLOCK(1)
;   float pmax = pm0;
; #pragma unroll
;   for (int r = 0; r < 16; ++r) pmax = fmaxf(pmax, p1[r]);
;   { auto rr = __builtin_amdgcn_permlane32_swap(__float_as_uint(pmax), __float_as_uint(pmax), false, false);
;     pmax = fmaxf(__uint_as_float(rr[0]), __uint_as_float(rr[1])); }
;   const bool keep = __all(pmax - m_reg <= ATH);
;   mn = keep ? m_reg : fmaxf(m_reg, pmax);
;   alpha = __builtin_amdgcn_exp2f(m_reg - mn);
;   m_reg = mn;
;   PV_BLOCK(2)
; #pragma unroll
;   for (int r = 0; r < 16; ++r) { p0[r] = p0[r] - mn; p1[r] = p1[r] - mn; }
;   PV_BLOCK(3)
; #pragma unroll
;   for (int r = 0; r < 16; ++r) p0[r] = __builtin_amdgcn_exp2f(p0[r]);
; }
	v_mfma_f32_32x32x16_bf16 v[2:17], v[194:197], v[226:229], v[2:17]
	v_mfma_f32_32x32x16_bf16 v[50:65], v[130:133], v[214:217], v[50:65]
	v_max3_f32 v144, v144, v66, v67
	v_max3_f32 v144, v144, v68, v69
	v_max3_f32 v144, v144, v70, v71
	v_max3_f32 v144, v144, v72, v73
	v_max3_f32 v144, v144, v74, v75
	v_max3_f32 v144, v144, v76, v77
	v_max3_f32 v144, v144, v78, v79
	v_mfma_f32_32x32x16_bf16 v[50:65], v[186:189], v[218:221], v[50:65]
	v_max3_f32 v144, v144, v80, v81
	v_mov_b32_e32 v157, v144
	s_nop 1
	v_permlane32_swap_b32_e32 v144, v157
	v_max_f32_e32 v157, v157, v157
	v_max_f32_e32 v144, v144, v144
	v_max_f32_e32 v144, v144, v157
	v_mfma_f32_32x32x16_bf16 v[50:65], v[190:193], v[222:225], v[50:65]
	ds_read_b64_tr_b16 v[214:215], v156 offset:0x400
	v_sub_f32_e32 v157, v144, v153
	ds_read_b64_tr_b16 v[216:217], v156 offset:0xc00
	v_cmp_ge_f32_e32 vcc, s54, v157
	ds_read_b64_tr_b16 v[218:219], v156 offset:0x1400
	s_cmp_eq_u64 vcc, exec
	v_max_f32_e32 v157, v153, v153
	ds_read_b64_tr_b16 v[220:221], v156 offset:0x1c00
	v_mfma_f32_32x32x16_bf16 v[50:65], v[194:197], v[230:233], v[50:65]
	v_max_f32_e32 v144, v157, v144
	s_cselect_b64 vcc, -1, 0
	ds_read_b64_tr_b16 v[222:223], v156 offset:0x2400
	v_cndmask_b32_e32 v144, v144, v153, vcc
	ds_read_b64_tr_b16 v[224:225], v156 offset:0x2c00
	v_sub_f32_e32 v153, v153, v144
	ds_read_b64_tr_b16 v[226:227], v156 offset:0x3400
	v_exp_f32_e32 v184, v153
	ds_read_b64_tr_b16 v[228:229], v156 offset:0x3c00
	s_waitcnt lgkmcnt(0)
	v_mfma_f32_32x32x16_bf16 v[34:49], v[130:133], v[214:217], v[34:49]
	ds_read_b64_tr_b16 v[214:215], v156 offset:0x600
	ds_read_b64_tr_b16 v[216:217], v156 offset:0xe00
	v_sub_f32_e32 v82, v82, v144
	v_sub_f32_e32 v83, v83, v144
	v_sub_f32_e32 v84, v84, v144
	v_sub_f32_e32 v85, v85, v144
	v_mfma_f32_32x32x16_bf16 v[34:49], v[186:189], v[218:221], v[34:49]
	ds_read_b64_tr_b16 v[218:219], v156 offset:0x1600
	ds_read_b64_tr_b16 v[220:221], v156 offset:0x1e00
	v_sub_f32_e32 v86, v86, v144
	v_sub_f32_e32 v87, v87, v144
	v_exp_f32_e32 v240, v82
	v_exp_f32_e32 v241, v83
	v_mfma_f32_32x32x16_bf16 v[34:49], v[190:193], v[222:225], v[34:49]
	ds_read_b64_tr_b16 v[222:223], v156 offset:0x2600
	ds_read_b64_tr_b16 v[224:225], v156 offset:0x2e00
	ds_read_b64_tr_b16 v[230:231], v156 offset:0x3600
	ds_read_b64_tr_b16 v[232:233], v156 offset:0x3e00
	v_sub_f32_e32 v88, v88, v144
	v_sub_f32_e32 v89, v89, v144
	v_exp_f32_e32 v242, v84
	v_exp_f32_e32 v243, v85
	s_waitcnt lgkmcnt(0)
	v_mfma_f32_32x32x16_bf16 v[34:49], v[194:197], v[226:229], v[34:49]
	v_sub_f32_e32 v90, v90, v144
	v_sub_f32_e32 v91, v91, v144
	v_exp_f32_e32 v244, v86
	v_exp_f32_e32 v245, v87
	v_mfma_f32_32x32x16_bf16 v[18:33], v[130:133], v[214:217], v[18:33]
	v_sub_f32_e32 v92, v92, v144
	v_sub_f32_e32 v93, v93, v144
	v_exp_f32_e32 v246, v88
	v_exp_f32_e32 v247, v89
	s_add_i32 s9, s8, 0
	v_add_u32_e32 v130, s9, v164
	s_waitcnt vmcnt(0)
	s_waitcnt vmcnt(4)
	ds_write_b128 v130, v[198:201]
	v_add_u32_e32 v130, s9, v165
	s_waitcnt vmcnt(2)
	ds_write_b128 v130, v[206:209]
	v_add_u32_e32 v130, s9, v167
	v_mfma_f32_32x32x16_bf16 v[18:33], v[186:189], v[218:221], v[18:33]
	ds_write_b128 v130, v[202:205] offset:16384
	v_add_u32_e32 v130, s9, v168
	s_waitcnt vmcnt(1)
	ds_write_b128 v130, v[210:213] offset:16384
	v_add_u32_e32 v130, s9, v169
	v_cmp_gt_f32_e32 vcc, 1.0, v184
	s_waitcnt vmcnt(0)
	ds_write_b128 v130, v[146:149] offset:32768
	v_sub_f32_e32 v94, v94, v144
	v_sub_f32_e32 v95, v95, v144
	v_exp_f32_e32 v248, v90
	v_exp_f32_e32 v249, v91
	v_mfma_f32_32x32x16_bf16 v[18:33], v[190:193], v[222:225], v[18:33]
	v_sub_f32_e32 v96, v96, v144
	v_sub_f32_e32 v97, v97, v144
	v_exp_f32_e32 v250, v92
	v_exp_f32_e32 v251, v93
	v_mfma_f32_32x32x16_bf16 v[18:33], v[194:197], v[230:233], v[18:33]
	v_exp_f32_e32 v252, v94
	v_exp_f32_e32 v253, v95
	v_exp_f32_e32 v254, v96
	v_exp_f32_e32 v255, v97
	s_cbranch_vccz .LBB0_673
	s_and_saveexec_b64 s[4:5], s[2:3]
	ds_write_b32 v161, v184 offset:128
	s_or_b64 exec, exec, s[4:5]
	s_waitcnt lgkmcnt(0)
	v_add_u32_e32 v153, v137, v134
	ds_read_b128 v[130:133], v153 offset:224
	ds_read_b128 v[146:149], v153 offset:192
	ds_read_b128 v[186:189], v153 offset:160
	ds_read_b128 v[190:193], v153 offset:128
	s_waitcnt lgkmcnt(3)
	v_pk_mul_f32 v[14:15], v[14:15], v[130:131]
	s_waitcnt lgkmcnt(2)
	v_pk_mul_f32 v[10:11], v[10:11], v[146:147]
	s_waitcnt lgkmcnt(1)
	v_pk_mul_f32 v[6:7], v[6:7], v[186:187]
	v_pk_mul_f32 v[16:17], v[16:17], v[132:133]
	v_pk_mul_f32 v[12:13], v[12:13], v[148:149]
	v_pk_mul_f32 v[8:9], v[8:9], v[188:189]
	s_waitcnt lgkmcnt(0)
	v_pk_mul_f32 v[4:5], v[4:5], v[192:193]
	v_pk_mul_f32 v[2:3], v[2:3], v[190:191]
	v_pk_mul_f32 v[62:63], v[62:63], v[130:131]
	v_pk_mul_f32 v[58:59], v[58:59], v[146:147]
	v_pk_mul_f32 v[54:55], v[54:55], v[186:187]
	v_pk_mul_f32 v[64:65], v[64:65], v[132:133]
	v_pk_mul_f32 v[60:61], v[60:61], v[148:149]
	v_pk_mul_f32 v[56:57], v[56:57], v[188:189]
	v_pk_mul_f32 v[52:53], v[52:53], v[192:193]
	v_pk_mul_f32 v[50:51], v[50:51], v[190:191]
	v_pk_mul_f32 v[46:47], v[46:47], v[130:131]
	v_pk_mul_f32 v[42:43], v[42:43], v[146:147]
	v_pk_mul_f32 v[38:39], v[38:39], v[186:187]
	v_pk_mul_f32 v[48:49], v[48:49], v[132:133]
	v_pk_mul_f32 v[44:45], v[44:45], v[148:149]
	v_pk_mul_f32 v[40:41], v[40:41], v[188:189]
	v_pk_mul_f32 v[36:37], v[36:37], v[192:193]
	v_pk_mul_f32 v[34:35], v[34:35], v[190:191]
	v_pk_mul_f32 v[30:31], v[30:31], v[130:131]
	v_pk_mul_f32 v[26:27], v[26:27], v[146:147]
	v_pk_mul_f32 v[22:23], v[22:23], v[186:187]
	v_pk_mul_f32 v[32:33], v[32:33], v[132:133]
	v_pk_mul_f32 v[28:29], v[28:29], v[148:149]
	v_pk_mul_f32 v[24:25], v[24:25], v[188:189]
	v_pk_mul_f32 v[20:21], v[20:21], v[192:193]
	v_pk_mul_f32 v[18:19], v[18:19], v[190:191]
